# down-proj rounds visit row tiles from high to low (reuse of just-written hidden activations in memory-side cache); on top of in-proj 4x8 order
# speedup vs baseline: 1.0032x; 1.0032x over previous
;     __host__ __device__ bool next(int i, Unit& u) const {
;     ...
;         int wgid = ex ? 0 : L; { const int q = nwg / NXCD, r = nwg % NXCD, xcd = wgid % NXCD, off = wgid / NXCD; wgid = (xcd < r ? xcd * (q + 1) : r * (q + 1) + (xcd - r) * q) + off; }
;         const int nig = WGM * nN, gid = wgid / nig, fm = gid * WGM, gsz = (nM - fm) < WGM ? (nM - fm) : WGM;
;         int pm_m = fm + ((wgid % nig) % gsz), pn_m = (wgid % nig) / gsz;
;         if (nN == 16 && G == 256) {
;             const int xcd = c & 7, j = c >> 3; pm_m = 8 * (2 * i + (xcd >> 2)) + (j & 7); pn_m = 4 * (xcd & 3) + (j >> 3); }
;         if (nN == 64 && G == 256) {
;             const int xcd = c & 7, j = c >> 3; pm_m = 4 * i + (j & 3); pn_m = 8 * xcd + (j >> 2); }
;         const int nk_e = nt / split;
;         u.pm = ex ? 96 : pm_m; u.pn = ex ? e / split : pn_m; u.nkt = ex ? nk_e : nt; u.kt0 = ex ? (e % split) * nk_e : 0;
.LBB0_1402:
	s_add_i32 s83, s83, 1
	s_mul_i32 s4, s83, s33
	s_add_i32 s4, s4, s2
	s_cmpk_lt_i32 s4, 0x700
	s_cselect_b64 s[46:47], -1, 0
	s_cmpk_gt_i32 s4, 0x6ff
	s_cbranch_scc1 .LBB0_1405
	s_cmpk_lt_i32 s4, 0x600
	s_cselect_b64 s[40:41], -1, 0
	s_and_b64 vcc, s[40:41], exec
	s_cselect_b32 s5, s4, 0
	s_ashr_i32 s7, s5, 31
	s_lshr_b32 s7, s7, 29
	s_add_i32 s7, s5, s7
	s_ashr_i32 s40, s7, 3
	s_and_b32 s7, s7, -8
	s_sub_i32 s5, s5, s7
	s_cmp_lt_i32 s5, 0
	s_cselect_b32 s7, s74, 0xc0
	s_mul_i32 s5, s5, s7
	s_add_i32 s5, s5, s40
	s_ashr_i32 s7, s5, 31
	s_lshr_b32 s7, s7, 25
	s_add_i32 s7, s5, s7
	s_ashr_i32 s40, s7, 7
	s_lshl_b32 s41, s40, 3
	s_sub_i32 s40, 0x60, s41
	s_min_u32 s44, s40, 8
	s_and_b32 s7, s7, 0xffffff80
	s_sub_i32 s5, s5, s7
	s_waitcnt lgkmcnt(0)
	v_cvt_f32_ubyte0_e32 v1, s44
	v_cvt_f32_i32_e32 v0, s5
	v_rcp_iflag_f32_e32 v2, v1
	s_ashr_i32 s7, s5, 30
	s_or_b32 s7, s7, 1
	s_mov_b32 s40, 0
	v_mul_f32_e32 v2, v0, v2
	v_trunc_f32_e32 v2, v2
	v_fma_f32 v0, -v2, v1, v0
	v_cvt_i32_f32_e32 v2, v2
	v_cmp_ge_f32_e64 s[42:43], |v0|, v1
	s_and_b64 s[42:43], s[42:43], exec
	s_cselect_b32 s7, s7, 0
	v_readfirstlane_b32 s42, v2
	s_add_i32 s7, s42, s7
	s_sext_i32_i8 s45, s7
	s_mul_i32 s7, s7, s44
	s_sub_i32 s5, s5, s7
	s_sext_i32_i8 s5, s5
	s_add_i32 s41, s41, s5
	s_sub_i32 s5, 5, s83
	s_lshl_b32 s5, s5, 4
	s_or_b32 s5, s5, s72
	s_and_b64 s[42:43], s[22:23], exec
	s_cselect_b32 s42, s73, s45
	s_cselect_b32 s44, s5, s41
	s_movk_i32 s84, 0x100
	s_cbranch_vccnz .LBB0_1405
	s_bfe_u32 s42, s4, 0x40004
	s_lshl_b32 s4, s4, 4
	s_and_b32 s40, s4, 0xf0
	s_mov_b32 s84, 16
	s_movk_i32 s44, 0x60

;     __host__ __device__ bool next(int i, Unit& u) const {
;     ...
;         if (nN == 16 && G == 256) {
;             const int xcd = c & 7, j = c >> 3; pm_m = 8 * (2 * i + (xcd >> 2)) + (j & 7); pn_m = 4 * (xcd & 3) + (j >> 3); }
.LBB0_1469:
.LBB0_1470:
	s_lshl_b32 s6, s2, 1
	s_and_b32 s6, s6, 8
	s_bfe_u32 s7, s2, 0x30003
	s_or_b32 s6, s6, s7
	s_addk_i32 s6, 0x50
	s_lshl_b32 s7, s2, 2
	s_and_b32 s7, s7, 12
	s_ashr_i32 s8, s2, 6
	s_add_i32 s8, s7, s8
